# GEMM1a tile order: every XCD owns 4 row panels, all XCDs sweep the same 8 column panels per round (the source's alternative order; pm=4*(bx&7)+((bx>>3)&3), pn=8*round+(bx>>5)); on top of v064
# speedup vs baseline: 1.0047x; 1.0047x over previous
; #define PG8_STAGE(bufoff, gbase) do { _Pragma("unroll") for (int _i = 0; _i < 2; ++_i) \
;         __builtin_amdgcn_global_load_lds((const unsigned*)((const char*)(gbase) + voffA[_i]), (LAS unsigned*)(lds + (bufoff) + ldsw + _i * 8192), 16, 0, 0); } while (0)
; #define PG8_BAR __builtin_amdgcn_s_barrier()
;     __device__ bool next(int i, Unit& u) const {
;     ...
;         if (G == 256 && nM == 32 && (nN & 7) == 0) {
;             if (ti >= (nN >> 3)) return false;
;             const int x = c & 7, j = c >> 3; u.pm = 4 * x + (j & 3); u.pn = 8 * ti + (j >> 2); return true;
;         }
; template <class Epi, class Sched, bool FP8 = false>
; __device__ __forceinline__ void gemm_phase(LAS unsigned char* lds, const Gemm g, const Sched& S, const Epi& E, const int tid) {
;     ...
;     for (int i = 0; i < 2; ++i) { int R, C; stage_rc(tid * 16 + i * 8192, R, C); voffA[i] = (unsigned)(R * K + C) * 2u; }
;     const size_t kstep = (size_t)(BK * 2);
;     const size_t hstep = (size_t)HALF * K * 2;
;     const size_t tstep = 2 * hstep;
;     const unsigned ldsw = (unsigned)wid * 1024u;
;     const int aoff = lds_byte(wr * 64 + fr, fq * 8), boff = lds_byte(wc * 32 + fr, fq * 8);
;     ...
;     Unit cur, nxt; int ui = 0;
;     if (!S.next(0, cur)) return;
;     f32x4 acc[2][2][4][2];
; #pragma unroll
;     for (int a = 0; a < 2; ++a)
; #pragma unroll
;         for (int b = 0; b < 2; ++b)
; #pragma unroll
;             for (int m = 0; m < 4; ++m)
; #pragma unroll
;                 for (int n = 0; n < 2; ++n) acc[a][b][m][n] = (f32x4){0.f, 0.f, 0.f, 0.f};
;     h16x8 At[4][2], B0[2][2], B1[2][2];
;     const char* cA = (const char*)g.A + (size_t)cur.pm * tstep + cur.half * halfb; const char* cB = (const char*)g.Bt + (size_t)cur.pn * tstep + cur.half * halfb;
;     PG8_STAGE(PG8_SB(0, 0), cB); PG8_STAGE(PG8_SB(0, 1), cB + hstep); PG8_STAGE(PG8_SA(0, 0), cA); PG8_STAGE(PG8_SA(0, 1), cA + hstep);
;     if (wr == 1) PG8_BAR;
.LBB0_88:
	s_and_b32 s4, s2, 7
	s_lshl_b32 s4, s4, 2
	s_bfe_u32 s5, s2, 0x20003
	s_or_b32 s4, s4, s5
	s_lshr_b32 s18, s2, 5
	s_andn2_b64 vcc, exec, s[0:1]
	s_ashr_i32 s31, s30, 31
	s_cbranch_vccnz .LBB0_144
	v_ashrrev_i32_e32 v2, 31, v0
	v_lshrrev_b32_e32 v2, 26, v2
	v_lshlrev_b32_e32 v1, 4, v0
	v_add_u32_e32 v2, v0, v2
	v_bfe_i32 v0, v0, 27, 1
	v_lshrrev_b32_e32 v0, 22, v0
	v_add_u32_e32 v0, v1, v0
	v_and_b32_e32 v0, 0xfffffc00, v0
	v_sub_u32_e32 v0, v1, v0
	v_ashrrev_i32_e32 v9, 6, v2
	v_lshrrev_b32_e32 v2, 4, v0
	v_bitop3_b32 v0, v2, v0, 32 bitop3:0x6c
	v_ashrrev_i32_e32 v3, 31, v0
	v_lshrrev_b32_e32 v3, 26, v3
	v_add_u32_e32 v3, v0, v3
	v_ashrrev_i32_e32 v10, 6, v3
	v_and_b32_e32 v3, 0xc0, v3
	v_sub_u32_e32 v0, v0, v3
	v_mov_b32_e32 v3, 1
	v_lshlrev_b32_e32 v2, 3, v9
	v_lshlrev_b32_e32 v4, 5, v9
	v_ashrrev_i16_sdwa v0, v3, sext(v0) dst_sel:DWORD dst_unused:UNUSED_PAD src0_sel:DWORD src1_sel:BYTE_0
	v_and_b32_e32 v2, 0x7fff0, v2
	v_and_b32_e32 v4, 32, v4
	v_bfe_i32 v11, v0, 0, 16
	v_add_u32_e32 v0, v4, v11
	v_add_lshl_u32 v2, v10, v2, 13
	v_lshl_add_u32 v128, v0, 1, v2
	v_mbcnt_lo_u32_b32 v239, -1, 0
	v_mbcnt_hi_u32_b32 v239, -1, v239
	s_lshr_b32 s92, s33, 6
	s_lshl_b32 s93, s92, 3
	s_and_b32 s94, s92, 1
	s_lshl_b32 s94, s94, 2
	v_lshrrev_b32_e32 v236, 3, v239
	v_add_u32_e32 v236, s93, v236
	v_lshrrev_b32_e32 v237, 4, v239
	v_add_u32_e32 v237, s94, v237
	v_and_b32_e32 v238, 7, v239
	v_xor_b32_e32 v237, v238, v237
	v_lshlrev_b32_e32 v237, 4, v237
	v_lshl_add_u32 v128, v236, 13, v237
	v_add_u32_e32 v0, 0x2000, v1
	v_ashrrev_i32_e32 v1, 31, v0
	v_lshrrev_b32_e32 v1, 22, v1
	v_add_u32_e32 v1, v0, v1
	v_ashrrev_i32_e32 v12, 10, v1
	v_mul_i32_i24_e32 v1, 0x400, v12
	v_sub_u32_e32 v0, v0, v1
	v_lshrrev_b32_e32 v1, 4, v0
	s_add_u32 s54, s53, 0x200000
	v_bitop3_b32 v0, v1, v0, 32 bitop3:0x6c
	s_addc_u32 s55, s7, 0
	v_ashrrev_i32_e32 v2, 31, v0
	s_add_u32 s56, s53, 0x10200000
	v_lshrrev_b32_e32 v2, 26, v2
	s_addc_u32 s57, s7, 0
	s_ashr_i32 s0, s16, 6
	v_add_u32_e32 v2, v0, v2
	s_ashr_i32 s5, s4, 31
	s_ashr_i32 s19, s18, 31
	v_ashrrev_i32_e32 v13, 6, v2
	v_and_b32_e32 v2, 0xc0, v2
	s_ashr_i32 s1, s16, 8
	s_lshl_b32 s58, s0, 10
	s_lshl_b64 s[10:11], s[4:5], 21
	s_lshl_b64 s[12:13], s[18:19], 21
	v_sub_u32_e32 v0, v0, v2
	s_add_u32 s48, s54, s12
	v_lshlrev_b32_e32 v1, 3, v12
	v_lshlrev_b32_e32 v4, 5, v12
	v_ashrrev_i16_sdwa v0, v3, sext(v0) dst_sel:DWORD dst_unused:UNUSED_PAD src0_sel:DWORD src1_sel:BYTE_0
	s_addc_u32 s49, s55, s13
	s_add_i32 s19, s58, 0
	v_and_b32_e32 v1, 0x7fff0, v1
	v_and_b32_e32 v4, 32, v4
	v_bfe_i32 v14, v0, 0, 16
	s_add_i32 m0, s19, 0x10000
	v_add_u32_e32 v0, v4, v14
	v_add_lshl_u32 v1, v13, v1, 13
	global_load_lds_dwordx4 v128, s[48:49]
	s_add_i32 m0, s19, 0x12000
	v_lshl_add_u32 v130, v0, 1, v1
	v_add_u32_e32 v130, 0x80000, v128
	s_add_u32 s12, s48, 0x100000
	global_load_lds_dwordx4 v130, s[48:49]
	s_addc_u32 s13, s49, 0
	s_add_i32 m0, s19, 0x14000
	v_mov_b32_e32 v129, 0
	global_load_lds_dwordx4 v128, s[12:13]
	s_add_i32 m0, s19, 0x16000
	s_add_u32 s46, s56, s10
	s_addc_u32 s47, s57, s11
	s_add_i32 s59, s19, 0x2000
	global_load_lds_dwordx4 v130, s[12:13]
	s_mov_b32 m0, s19
	s_add_u32 s10, s46, 0x100000
	global_load_lds_dwordx4 v128, s[46:47]
	s_mov_b32 m0, s59
	s_addc_u32 s11, s47, 0
	s_add_i32 s60, s19, 0x4000
	global_load_lds_dwordx4 v130, s[46:47]
	s_mov_b32 m0, s60
	s_add_i32 s61, s19, 0x6000
	global_load_lds_dwordx4 v128, s[10:11]
	s_mov_b32 m0, s61
	v_mov_b32_e32 v131, v129
	global_load_lds_dwordx4 v130, s[10:11]
	s_cmp_eq_u32 s1, 1
	s_mov_b64 s[10:11], 0x200000
	s_mov_b32 s62, 0
	v_lshl_add_u64 v[6:7], s[48:49], 0, v[128:129]
	v_lshl_add_u64 v[4:5], s[48:49], 0, v[130:131]
	v_lshl_add_u64 v[0:1], s[46:47], 0, v[128:129]
	s_cselect_b64 s[12:13], -1, 0
	s_cmp_lg_u32 s1, 1
	v_lshl_add_u64 v[2:3], s[46:47], 0, v[130:131]
	s_cbranch_scc1 .LBB0_91
	s_barrier

;     __device__ bool next(int i, Unit& u) const {
;         const int ti = halves == 2 ? (i >> 1) : i; u.half = halves == 2 ? (i & 1) : 0;
;     ...
;         if (G == 256 && nM == 32 && (nN & 7) == 0) {
;             if (ti >= (nN >> 3)) return false;
;             const int x = c & 7, j = c >> 3; u.pm = 4 * x + (j & 3); u.pn = 8 * ti + (j >> 2); return true;
;         }
;     ...
;         const long L = (long)ti * G + c; if (L >= nwg) return false;
;         int wgid = (int)L; { const int q = nwg / NXCD, r = nwg % NXCD, xcd = wgid % NXCD, off = wgid / NXCD; wgid = (xcd < r ? xcd * (q + 1) : r * (q + 1) + (xcd - r) * q) + off; }
;         const int nig = wgm * nN, gid = wgid / nig, fm = gid * wgm, gsz = (nM - fm) < wgm ? (nM - fm) : wgm;
;         u.pm = fm + ((wgid % nig) % gsz); u.pn = (wgid % nig) / gsz; return true;
.LBB0_99:
	s_ashr_i32 s5, s5, 3
	s_add_i32 s5, s29, s5
	s_ashr_i32 s26, s5, 31
	s_lshr_b32 s26, s26, 23
	s_add_i32 s26, s5, s26
	s_ashr_i32 s27, s26, 9
	s_lshl_b32 s27, s27, 3
	s_sub_i32 s28, 32, s27
	s_min_i32 s28, s28, 8
	s_abs_i32 s29, s28
	v_cvt_f32_u32_e32 v0, s29
	s_sub_i32 s43, 0, s29
	s_and_b32 s26, s26, 0xfffffe00
	s_sub_i32 s5, s5, s26
	v_rcp_iflag_f32_e32 v0, v0
	s_abs_i32 s26, s5
	s_xor_b32 s42, s5, s28
	s_ashr_i32 s42, s42, 31
	v_mul_f32_e32 v0, 0x4f7ffffe, v0
	v_cvt_u32_f32_e32 v0, v0
	s_nop 0
	v_readfirstlane_b32 s44, v0
	s_mul_i32 s43, s43, s44
	s_mul_hi_u32 s43, s44, s43
	s_add_i32 s44, s44, s43
	s_mul_hi_u32 s43, s26, s44
	s_mul_i32 s44, s43, s29
	s_sub_i32 s26, s26, s44
	s_add_i32 s45, s43, 1
	s_sub_i32 s44, s26, s29
	s_cmp_ge_u32 s26, s29
	s_cselect_b32 s43, s45, s43
	s_cselect_b32 s26, s44, s26
	s_add_i32 s44, s43, 1
	s_cmp_ge_u32 s26, s29
	s_cselect_b32 s26, s44, s43
	s_xor_b32 s26, s26, s42
	s_sub_i32 s26, s26, s42
	s_mul_i32 s28, s26, s28
	s_sub_i32 s5, s5, s28
	s_add_i32 s28, s27, s5
	s_and_b32 s28, s2, 7
	s_lshl_b32 s28, s28, 2
	s_bfe_u32 s5, s2, 0x20003
	s_or_b32 s28, s28, s5
	s_lshl_b32 s26, s62, 3
	s_lshr_b32 s5, s2, 5
	s_add_i32 s26, s26, s5
